# out-proj context setup: kernarg pointer load skipped in layers where its value is unused
# speedup vs baseline: 1.0085x; 1.0017x over previous
.LBB0_1090:
	v_readlane_b32 s0, v255, 13
	v_readlane_b32 s1, v255, 14
	s_and_b64 s[0:1], s[0:1], exec
	s_cselect_b32 s44, 0, 0x100
	s_cmp_lt_i32 s72, s44
	s_cselect_b64 s[0:1], -1, 0
	v_mov_b32_e32 v2, v220
	v_readlane_b32 s4, v254, 0
	v_writelane_b32 v255, s0, 23
	v_readlane_b32 s5, v254, 1
	v_readfirstlane_b32 s7, v2
	v_writelane_b32 v255, s1, 24
	s_cmp_ge_i32 s72, s44
	s_mov_b64 s[18:19], 0x2000000
	s_cbranch_scc1 .LBB0_1093
	v_readlane_b32 s6, v255, 8
	s_cmp_lg_u32 s6, 0
	s_cbranch_scc1 .Lctxd_noptr
	global_load_dwordx2 v[4:5], v221, s[4:5] offset:16
.Lctxd_noptr:
	s_add_u32 s0, s4, 0x100000
	s_addc_u32 s1, s5, 0
	v_readlane_b32 s3, v255, 7
	s_add_u32 s3, s4, s3
	s_addc_u32 s6, s5, 0
	s_add_u32 s3, s3, 0x400000
	s_addc_u32 s6, s6, 0
	v_readlane_b32 s8, v255, 8
	s_cmp_eq_u32 s8, 0
	v_readlane_b32 s8, v255, 19
	v_readlane_b32 s9, v255, 20
	s_cselect_b64 vcc, -1, 0
	v_mov_b32_e32 v0, s1
	s_lshl_b64 s[8:9], s[8:9], 2
	s_add_u32 s8, s4, s8
	v_lshrrev_b32_e32 v6, 1, v2
	s_addc_u32 s9, s5, s9
	s_ashr_i32 s10, s7, 6
	v_and_b32_e32 v3, 15, v2
	v_and_b32_e32 v45, 48, v2
	s_lshl_b32 s7, s10, 2
	v_ashrrev_i32_e32 v51, 4, v2
	v_or_b32_e32 v48, 0x1000, v45
	v_readlane_b32 s13, v254, 23
	s_mov_b32 s14, s72
	s_waitcnt vmcnt(0)
	v_cndmask_b32_e32 v35, v0, v5, vcc
	v_mov_b32_e32 v0, s0
	v_cndmask_b32_e32 v34, v0, v4, vcc
	v_and_b32_e32 v0, 24, v6
	v_lshl_or_b32 v4, s10, 7, v0
	v_ashrrev_i32_e32 v5, 31, v4
	v_lshl_add_u64 v[4:5], v[4:5], 1, s[4:5]
	v_lshlrev_b32_e32 v0, 11, v3
	v_lshl_add_u64 v[4:5], v[4:5], 0, v[0:1]
	s_mov_b64 s[4:5], 0xb1c0000
	v_lshl_add_u64 v[36:37], v[4:5], 0, s[4:5]
	v_and_b32_e32 v4, 3, v2
	v_and_or_b32 v4, v6, 4, v4
	v_lshlrev_b32_e32 v46, 6, v4
	s_lshl_b32 s4, s10, 1
	v_lshlrev_b32_e32 v0, 2, v2
	v_or_b32_e32 v47, 0x200, v46
	s_or_b32 s12, s4, 1
	s_lshl_b32 s4, s10, 13
	v_or_b32_e32 v4, v45, v47
	s_add_i32 s4, s4, 0
	v_and_b32_e32 v52, 60, v0
	v_and_b32_e32 v44, 16, v0
	v_or_b32_e32 v49, 0x400, v4
	v_or_b32_e32 v50, 0x1400, v4
	v_lshlrev_b32_e32 v3, 8, v3
	v_add_u32_e32 v4, s4, v45
	v_lshlrev_b32_e32 v0, 8, v51
	v_lshlrev_b32_e32 v2, 2, v52
	s_add_u32 s4, s8, 0xe000
	v_add3_u32 v53, 0, v0, v2
	s_addc_u32 s5, s9, 0
	v_add_u32_e32 v54, v4, v3
